# attention-prep lane exchanges via DPP/permlane swaps instead of LDS bpermute; adaLN projection weights software-prefetched one k-step ahead
# speedup vs baseline: 1.0909x; 1.0071x over previous
; __device__ void phase0(const Params& P, unsigned char* smem, int bid, int nb) {
;     ...
;       float acc[17];
; #pragma unroll
;       for (int r = 0; r < 17; ++r) acc[r] = 0.f;
;       const float* w = P.ada_w + ((size_t)l * 1024 + kq * 256) * 6144 + col0 + col;
; #pragma unroll 2
;       for (int k = 0; k < 256; k += 4) {
;         float w0 = w[(size_t)(k + 0) * 6144], w1 = w[(size_t)(k + 1) * 6144], w2 = w[(size_t)(k + 2) * 6144], w3 = w[(size_t)(k + 3) * 6144];
; #pragma unroll
;         for (int r = 0; r < 17; ++r) {
;           float4 s = *(const float4*)(sc + r * 1024 + kq * 256 + k);
;           acc[r] += s.x * w0 + s.y * w1 + s.z * w2 + s.w * w3;
;         }
;       }
.LBB0_62:
	s_or_b64 exec, exec, s[26:27]
	s_mul_hi_i32 s0, s64, 0x2aaaaaab
	s_lshr_b32 s1, s0, 31
	s_ashr_i32 s2, s0, 4
	s_add_i32 s2, s2, s1
	s_mul_i32 s3, s2, 0x1800
	s_sub_i32 s0, s33, s3
	s_ashr_i32 s1, s0, 31
	s_mul_i32 s5, s2, 0x1800000
	s_lshl_b64 s[0:1], s[0:1], 2
	s_mul_hi_i32 s4, s2, 0x1800000
	s_add_u32 s0, s5, s0
	s_addc_u32 s1, s4, s1
	v_mov_b32_e32 v16, 0
	v_lshl_add_u64 v[6:7], v[36:37], 0, s[0:1]
	s_mov_b32 s0, -4
	v_mov_b32_e32 v78, v72
	v_mov_b32_e32 v8, 0
	v_mov_b32_e32 v9, v16
	v_mov_b32_e32 v64, 0
	v_mov_b32_e32 v65, v16
	v_mov_b32_e32 v62, 0
	v_mov_b32_e32 v63, v16
	v_mov_b32_e32 v60, 0
	v_mov_b32_e32 v61, v16
	v_mov_b32_e32 v58, 0
	v_mov_b32_e32 v59, v16
	v_mov_b32_e32 v56, 0
	v_mov_b32_e32 v57, v16
	v_mov_b32_e32 v12, 0
	v_mov_b32_e32 v13, v16
	v_mov_b32_e32 v10, 0
	v_mov_b32_e32 v11, v16
	s_waitcnt lgkmcnt(0)
	s_barrier
	v_add_co_u32_e32 v130, vcc, 0xfffd0000, v6
	s_nop 1
	v_addc_co_u32_e32 v131, vcc, -1, v7, vcc
	s_mov_b64 s[4:5], 0x6000
	v_lshl_add_u64 v[132:133], v[130:131], 0, s[4:5]
	global_load_dword v118, v[132:133], off
	s_mov_b64 s[4:5], 0xc000
	v_lshl_add_u64 v[132:133], v[130:131], 0, s[4:5]
	global_load_dword v119, v[132:133], off
	s_mov_b64 s[4:5], 0x12000
	v_lshl_add_u64 v[132:133], v[130:131], 0, s[4:5]
	global_load_dword v120, v[132:133], off
	s_mov_b64 s[4:5], 0x18000
	v_lshl_add_u64 v[132:133], v[130:131], 0, s[4:5]
	global_load_dword v121, v[132:133], off
	s_mov_b64 s[4:5], 0x1e000
	v_lshl_add_u64 v[132:133], v[130:131], 0, s[4:5]
	global_load_dword v122, v[132:133], off
	s_mov_b64 s[4:5], 0x24000
	v_lshl_add_u64 v[132:133], v[130:131], 0, s[4:5]
	global_load_dword v123, v[132:133], off
	s_mov_b64 s[4:5], 0x2a000
	v_lshl_add_u64 v[132:133], v[130:131], 0, s[4:5]
	global_load_dword v124, v[132:133], off
	s_mov_b64 s[4:5], 0x30000
	v_lshl_add_u64 v[132:133], v[130:131], 0, s[4:5]
	global_load_dword v125, v[132:133], off
.LBB0_63:
	s_waitcnt vmcnt(0)
	v_mov_b32_e32 v66, v118
	v_mov_b32_e32 v67, v119
	v_mov_b32_e32 v68, v120
	v_mov_b32_e32 v69, v121
	v_mov_b32_e32 v126, v122
	v_mov_b32_e32 v127, v123
	v_mov_b32_e32 v128, v124
	v_mov_b32_e32 v129, v125
	s_cmpk_lt_i32 s0, 0xf4
	s_cbranch_scc0 .Lmy_ph0_skip
	s_mov_b64 s[4:5], 0x6000
	v_lshl_add_u64 v[132:133], v[6:7], 0, s[4:5]
	global_load_dword v118, v[132:133], off
	s_mov_b64 s[4:5], 0xc000
	v_lshl_add_u64 v[132:133], v[6:7], 0, s[4:5]
	global_load_dword v119, v[132:133], off
	s_mov_b64 s[4:5], 0x12000
	v_lshl_add_u64 v[132:133], v[6:7], 0, s[4:5]
	global_load_dword v120, v[132:133], off
	s_mov_b64 s[4:5], 0x18000
	v_lshl_add_u64 v[132:133], v[6:7], 0, s[4:5]
	global_load_dword v121, v[132:133], off
	s_mov_b64 s[4:5], 0x1e000
	v_lshl_add_u64 v[132:133], v[6:7], 0, s[4:5]
	global_load_dword v122, v[132:133], off
	s_mov_b64 s[4:5], 0x24000
	v_lshl_add_u64 v[132:133], v[6:7], 0, s[4:5]
	global_load_dword v123, v[132:133], off
	s_mov_b64 s[4:5], 0x2a000
	v_lshl_add_u64 v[132:133], v[6:7], 0, s[4:5]
	global_load_dword v124, v[132:133], off
	s_mov_b64 s[4:5], 0x30000
	v_lshl_add_u64 v[132:133], v[6:7], 0, s[4:5]
	global_load_dword v125, v[132:133], off
.Lmy_ph0_skip:
	ds_read_b128 v[80:83], v78
	ds_read_b128 v[2:5], v78 offset:16
	s_add_i32 s0, s0, 8
	s_mov_b64 s[4:5], 0x30000
	s_cmpk_gt_u32 s0, 0xfb
	s_waitcnt lgkmcnt(1)
	v_pk_mul_f32 v[80:81], v[66:67], v[80:81]
	s_nop 0
	v_add_f32_e32 v22, v80, v81
	s_nop 0
	v_pk_mul_f32 v[82:83], v[68:69], v[82:83]
	s_nop 0
	v_add_f32_e32 v22, v22, v82
	v_add_f32_e32 v22, v22, v83
	ds_read_b128 v[80:83], v78 offset:4096
	ds_read_b128 v[84:87], v78 offset:8192
	v_add_f32_e32 v79, v16, v22
	v_mov_b32_e32 v16, v67
	v_mov_b32_e32 v22, v69
	s_waitcnt lgkmcnt(1)
	v_mov_b32_e32 v89, v80
	s_waitcnt lgkmcnt(0)
	v_mov_b32_e32 v80, v85
	v_mov_b32_e32 v88, v84
	v_pk_mul_f32 v[80:81], v[16:17], v[80:81] op_sel_hi:[0,1]
	v_pk_fma_f32 v[80:81], v[66:67], v[88:89], v[80:81] op_sel_hi:[0,1,1]
	v_mov_b32_e32 v84, v86
	v_mov_b32_e32 v85, v82
	v_pk_fma_f32 v[80:81], v[68:69], v[84:85], v[80:81] op_sel_hi:[0,1,1]
	v_mov_b32_e32 v82, v87
	v_pk_fma_f32 v[80:81], v[22:23], v[82:83], v[80:81] op_sel_hi:[0,1,1]
	v_pk_add_f32 v[10:11], v[10:11], v[80:81]
	ds_read_b128 v[80:83], v78 offset:12288
	ds_read_b128 v[84:87], v78 offset:16384
	s_waitcnt lgkmcnt(1)
	v_mov_b32_e32 v89, v80
	s_waitcnt lgkmcnt(0)
	v_mov_b32_e32 v80, v85
	v_mov_b32_e32 v88, v84
	v_pk_mul_f32 v[80:81], v[16:17], v[80:81] op_sel_hi:[0,1]
	v_pk_fma_f32 v[80:81], v[66:67], v[88:89], v[80:81] op_sel_hi:[0,1,1]
	v_mov_b32_e32 v84, v86
	v_mov_b32_e32 v85, v82
	v_pk_fma_f32 v[80:81], v[68:69], v[84:85], v[80:81] op_sel_hi:[0,1,1]
	v_mov_b32_e32 v82, v87
	v_pk_fma_f32 v[80:81], v[22:23], v[82:83], v[80:81] op_sel_hi:[0,1,1]
	v_pk_add_f32 v[12:13], v[12:13], v[80:81]
	ds_read_b128 v[80:83], v78 offset:20480
	ds_read_b128 v[84:87], v78 offset:24576
	s_waitcnt lgkmcnt(1)
	v_mov_b32_e32 v89, v80
	s_waitcnt lgkmcnt(0)
	v_mov_b32_e32 v80, v85
	v_mov_b32_e32 v88, v84
	v_pk_mul_f32 v[80:81], v[16:17], v[80:81] op_sel_hi:[0,1]
	v_pk_fma_f32 v[80:81], v[66:67], v[88:89], v[80:81] op_sel_hi:[0,1,1]
	v_mov_b32_e32 v84, v86
	v_mov_b32_e32 v85, v82
	v_pk_fma_f32 v[80:81], v[68:69], v[84:85], v[80:81] op_sel_hi:[0,1,1]
	v_mov_b32_e32 v82, v87
	v_pk_fma_f32 v[80:81], v[22:23], v[82:83], v[80:81] op_sel_hi:[0,1,1]
	v_pk_add_f32 v[56:57], v[56:57], v[80:81]
	ds_read_b128 v[80:83], v78 offset:28672
	ds_read_b128 v[84:87], v78 offset:32768
	s_waitcnt lgkmcnt(1)
	v_mov_b32_e32 v89, v80
	s_waitcnt lgkmcnt(0)
; __device__ void phase0(const Params& P, unsigned char* smem, int bid, int nb) {
;     ...
;       for (int k = 0; k < 256; k += 4) {
;         float w0 = w[(size_t)(k + 0) * 6144], w1 = w[(size_t)(k + 1) * 6144], w2 = w[(size_t)(k + 2) * 6144], w3 = w[(size_t)(k + 3) * 6144];
; #pragma unroll
;         for (int r = 0; r < 17; ++r) {
;           float4 s = *(const float4*)(sc + r * 1024 + kq * 256 + k);
;           acc[r] += s.x * w0 + s.y * w1 + s.z * w2 + s.w * w3;
;         }
	v_mov_b32_e32 v80, v85
	v_mov_b32_e32 v88, v84
	v_pk_mul_f32 v[80:81], v[16:17], v[80:81] op_sel_hi:[0,1]
	v_pk_fma_f32 v[80:81], v[66:67], v[88:89], v[80:81] op_sel_hi:[0,1,1]
	v_mov_b32_e32 v84, v86
	v_mov_b32_e32 v85, v82
	v_pk_fma_f32 v[80:81], v[68:69], v[84:85], v[80:81] op_sel_hi:[0,1,1]
	v_mov_b32_e32 v82, v87
	v_pk_fma_f32 v[80:81], v[22:23], v[82:83], v[80:81] op_sel_hi:[0,1,1]
	v_pk_add_f32 v[58:59], v[58:59], v[80:81]
	ds_read_b128 v[80:83], v78 offset:36864
	ds_read_b128 v[84:87], v78 offset:40960
	s_waitcnt lgkmcnt(1)
	v_mov_b32_e32 v89, v80
	s_waitcnt lgkmcnt(0)
	v_mov_b32_e32 v80, v85
	v_mov_b32_e32 v88, v84
	v_pk_mul_f32 v[80:81], v[16:17], v[80:81] op_sel_hi:[0,1]
	v_pk_fma_f32 v[80:81], v[66:67], v[88:89], v[80:81] op_sel_hi:[0,1,1]
	v_mov_b32_e32 v84, v86
	v_mov_b32_e32 v85, v82
	v_pk_fma_f32 v[80:81], v[68:69], v[84:85], v[80:81] op_sel_hi:[0,1,1]
	v_mov_b32_e32 v82, v87
	v_pk_fma_f32 v[80:81], v[22:23], v[82:83], v[80:81] op_sel_hi:[0,1,1]
	v_pk_add_f32 v[60:61], v[60:61], v[80:81]
	ds_read_b128 v[80:83], v78 offset:45056
	ds_read_b128 v[84:87], v78 offset:49152
	s_waitcnt lgkmcnt(1)
	v_mov_b32_e32 v89, v80
	s_waitcnt lgkmcnt(0)
	v_mov_b32_e32 v80, v85
	v_mov_b32_e32 v88, v84
	v_pk_mul_f32 v[80:81], v[16:17], v[80:81] op_sel_hi:[0,1]
	v_pk_fma_f32 v[80:81], v[66:67], v[88:89], v[80:81] op_sel_hi:[0,1,1]
	v_mov_b32_e32 v84, v86
	v_mov_b32_e32 v85, v82
	v_pk_fma_f32 v[80:81], v[68:69], v[84:85], v[80:81] op_sel_hi:[0,1,1]
	v_mov_b32_e32 v82, v87
	v_pk_fma_f32 v[80:81], v[22:23], v[82:83], v[80:81] op_sel_hi:[0,1,1]
	v_pk_add_f32 v[62:63], v[62:63], v[80:81]
	ds_read_b128 v[80:83], v78 offset:53248
	ds_read_b128 v[84:87], v78 offset:57344
	s_waitcnt lgkmcnt(1)
	v_mov_b32_e32 v89, v80
	s_waitcnt lgkmcnt(0)
	v_mov_b32_e32 v80, v85
	v_mov_b32_e32 v88, v84
	v_pk_mul_f32 v[80:81], v[16:17], v[80:81] op_sel_hi:[0,1]
	v_pk_fma_f32 v[80:81], v[66:67], v[88:89], v[80:81] op_sel_hi:[0,1,1]
	v_mov_b32_e32 v84, v86
	v_mov_b32_e32 v85, v82
	v_pk_fma_f32 v[80:81], v[68:69], v[84:85], v[80:81] op_sel_hi:[0,1,1]
	v_mov_b32_e32 v82, v87
	v_pk_fma_f32 v[80:81], v[22:23], v[82:83], v[80:81] op_sel_hi:[0,1,1]
	v_pk_add_f32 v[64:65], v[64:65], v[80:81]
	v_add_u32_e32 v67, 0x10000, v78
	ds_read_b128 v[80:83], v78 offset:61440
	ds_read_b128 v[84:87], v67
	s_waitcnt lgkmcnt(1)
	v_mov_b32_e32 v89, v80
	s_waitcnt lgkmcnt(0)
	v_mov_b32_e32 v80, v85
	v_mov_b32_e32 v88, v84
	v_pk_mul_f32 v[80:81], v[16:17], v[80:81] op_sel_hi:[0,1]
	v_pk_fma_f32 v[66:67], v[66:67], v[88:89], v[80:81] op_sel_hi:[0,1,1]
	v_mov_b32_e32 v80, v86
	v_mov_b32_e32 v81, v82
	v_pk_fma_f32 v[66:67], v[68:69], v[80:81], v[66:67] op_sel_hi:[0,1,1]
	v_mov_b32_e32 v82, v87
	v_pk_fma_f32 v[66:67], v[22:23], v[82:83], v[66:67] op_sel_hi:[0,1,1]
	v_pk_add_f32 v[8:9], v[8:9], v[66:67]
	v_mov_b32_e32 v66, v126
	v_mov_b32_e32 v67, v127
	v_pk_mul_f32 v[2:3], v[66:67], v[2:3]
	v_add_f32_e32 v2, v2, v3
	v_lshl_add_u64 v[6:7], v[6:7], 0, s[4:5]
	v_mov_b32_e32 v68, v128
	v_mov_b32_e32 v69, v129
	v_pk_mul_f32 v[4:5], v[68:69], v[4:5]
	s_nop 0
	v_add_f32_e32 v2, v2, v4
	v_add_f32_e32 v2, v2, v5
	v_add_f32_e32 v16, v79, v2
	ds_read_b128 v[80:83], v78 offset:4112
	ds_read_b128 v[2:5], v78 offset:8208
	s_waitcnt lgkmcnt(1)
	v_mov_b32_e32 v85, v80
	s_waitcnt lgkmcnt(0)
	v_mov_b32_e32 v84, v2
	v_mov_b32_e32 v2, v67
	v_mov_b32_e32 v80, v3
	v_pk_mul_f32 v[80:81], v[2:3], v[80:81] op_sel_hi:[0,1]
	v_pk_fma_f32 v[80:81], v[66:67], v[84:85], v[80:81] op_sel_hi:[0,1,1]
	v_mov_b32_e32 v84, v4
	v_mov_b32_e32 v85, v82
	v_pk_fma_f32 v[80:81], v[68:69], v[84:85], v[80:81] op_sel_hi:[0,1,1]
	v_mov_b32_e32 v4, v69
	v_mov_b32_e32 v82, v5
	v_pk_fma_f32 v[80:81], v[4:5], v[82:83], v[80:81] op_sel_hi:[0,1,1]
	v_pk_add_f32 v[10:11], v[10:11], v[80:81]
	ds_read_b128 v[80:83], v78 offset:12304
	ds_read_b128 v[84:87], v78 offset:16400
	s_waitcnt lgkmcnt(1)
	v_mov_b32_e32 v89, v80
	s_waitcnt lgkmcnt(0)
	v_mov_b32_e32 v80, v85
	v_mov_b32_e32 v88, v84
	v_pk_mul_f32 v[80:81], v[2:3], v[80:81] op_sel_hi:[0,1]
	v_pk_fma_f32 v[80:81], v[66:67], v[88:89], v[80:81] op_sel_hi:[0,1,1]
	v_mov_b32_e32 v84, v86
	v_mov_b32_e32 v85, v82
	v_pk_fma_f32 v[80:81], v[68:69], v[84:85], v[80:81] op_sel_hi:[0,1,1]
	v_mov_b32_e32 v82, v87
	v_pk_fma_f32 v[80:81], v[4:5], v[82:83], v[80:81] op_sel_hi:[0,1,1]
	v_pk_add_f32 v[12:13], v[12:13], v[80:81]
	ds_read_b128 v[80:83], v78 offset:20496
	ds_read_b128 v[84:87], v78 offset:24592
	s_waitcnt lgkmcnt(1)
; __device__ void phase0(const Params& P, unsigned char* smem, int bid, int nb) {
;     ...
;       for (int k = 0; k < 256; k += 4) {
;         float w0 = w[(size_t)(k + 0) * 6144], w1 = w[(size_t)(k + 1) * 6144], w2 = w[(size_t)(k + 2) * 6144], w3 = w[(size_t)(k + 3) * 6144];
; #pragma unroll
;         for (int r = 0; r < 17; ++r) {
;           float4 s = *(const float4*)(sc + r * 1024 + kq * 256 + k);
;           acc[r] += s.x * w0 + s.y * w1 + s.z * w2 + s.w * w3;
;         }
;       }
;       __syncthreads();
;       float* red = (float*)smem;
; #pragma unroll
;       for (int r = 0; r < 17; ++r) red[(kq * 17 + r) * 64 + col] = acc[r];
;       __syncthreads();
;       for (int i = tid; i < 17 * 64; i += 256) {
;         int r = i >> 6, cc = i & 63;
;         float s = red[(0 * 17 + r) * 64 + cc] + red[(1 * 17 + r) * 64 + cc] + red[(2 * 17 + r) * 64 + cc] + red[(3 * 17 + r) * 64 + cc];
;         P.mod[((size_t)(l * 17 + r)) * 6144 + col0 + cc] = s + P.ada_b[l * 6144 + col0 + cc];
	v_mov_b32_e32 v89, v80
	s_waitcnt lgkmcnt(0)
	v_mov_b32_e32 v80, v85
	v_mov_b32_e32 v88, v84
	v_pk_mul_f32 v[80:81], v[2:3], v[80:81] op_sel_hi:[0,1]
	v_pk_fma_f32 v[80:81], v[66:67], v[88:89], v[80:81] op_sel_hi:[0,1,1]
	v_mov_b32_e32 v84, v86
	v_mov_b32_e32 v85, v82
	v_pk_fma_f32 v[80:81], v[68:69], v[84:85], v[80:81] op_sel_hi:[0,1,1]
	v_mov_b32_e32 v82, v87
	v_pk_fma_f32 v[80:81], v[4:5], v[82:83], v[80:81] op_sel_hi:[0,1,1]
	v_pk_add_f32 v[56:57], v[56:57], v[80:81]
	ds_read_b128 v[80:83], v78 offset:28688
	ds_read_b128 v[84:87], v78 offset:32784
	s_waitcnt lgkmcnt(1)
	v_mov_b32_e32 v89, v80
	s_waitcnt lgkmcnt(0)
	v_mov_b32_e32 v80, v85
	v_mov_b32_e32 v88, v84
	v_pk_mul_f32 v[80:81], v[2:3], v[80:81] op_sel_hi:[0,1]
	v_pk_fma_f32 v[80:81], v[66:67], v[88:89], v[80:81] op_sel_hi:[0,1,1]
	v_mov_b32_e32 v84, v86
	v_mov_b32_e32 v85, v82
	v_pk_fma_f32 v[80:81], v[68:69], v[84:85], v[80:81] op_sel_hi:[0,1,1]
	v_mov_b32_e32 v82, v87
	v_pk_fma_f32 v[80:81], v[4:5], v[82:83], v[80:81] op_sel_hi:[0,1,1]
	v_pk_add_f32 v[58:59], v[58:59], v[80:81]
	ds_read_b128 v[80:83], v78 offset:36880
	ds_read_b128 v[84:87], v78 offset:40976
	s_waitcnt lgkmcnt(1)
	v_mov_b32_e32 v89, v80
	s_waitcnt lgkmcnt(0)
	v_mov_b32_e32 v80, v85
	v_mov_b32_e32 v88, v84
	v_pk_mul_f32 v[80:81], v[2:3], v[80:81] op_sel_hi:[0,1]
	v_pk_fma_f32 v[80:81], v[66:67], v[88:89], v[80:81] op_sel_hi:[0,1,1]
	v_mov_b32_e32 v84, v86
	v_mov_b32_e32 v85, v82
	v_pk_fma_f32 v[80:81], v[68:69], v[84:85], v[80:81] op_sel_hi:[0,1,1]
	v_mov_b32_e32 v82, v87
	v_pk_fma_f32 v[80:81], v[4:5], v[82:83], v[80:81] op_sel_hi:[0,1,1]
	v_pk_add_f32 v[60:61], v[60:61], v[80:81]
	ds_read_b128 v[80:83], v78 offset:45072
	ds_read_b128 v[84:87], v78 offset:49168
	s_waitcnt lgkmcnt(1)
	v_mov_b32_e32 v89, v80
	s_waitcnt lgkmcnt(0)
	v_mov_b32_e32 v80, v85
	v_mov_b32_e32 v88, v84
	v_pk_mul_f32 v[80:81], v[2:3], v[80:81] op_sel_hi:[0,1]
	v_pk_fma_f32 v[80:81], v[66:67], v[88:89], v[80:81] op_sel_hi:[0,1,1]
	v_mov_b32_e32 v84, v86
	v_mov_b32_e32 v85, v82
	v_pk_fma_f32 v[80:81], v[68:69], v[84:85], v[80:81] op_sel_hi:[0,1,1]
	v_mov_b32_e32 v82, v87
	v_pk_fma_f32 v[80:81], v[4:5], v[82:83], v[80:81] op_sel_hi:[0,1,1]
	v_pk_add_f32 v[62:63], v[62:63], v[80:81]
	ds_read_b128 v[80:83], v78 offset:53264
	ds_read_b128 v[84:87], v78 offset:57360
	s_waitcnt lgkmcnt(1)
	v_mov_b32_e32 v89, v80
	s_waitcnt lgkmcnt(0)
	v_mov_b32_e32 v80, v85
	v_mov_b32_e32 v88, v84
	v_pk_mul_f32 v[80:81], v[2:3], v[80:81] op_sel_hi:[0,1]
	v_pk_fma_f32 v[80:81], v[66:67], v[88:89], v[80:81] op_sel_hi:[0,1,1]
	v_mov_b32_e32 v84, v86
	v_mov_b32_e32 v85, v82
	v_pk_fma_f32 v[80:81], v[68:69], v[84:85], v[80:81] op_sel_hi:[0,1,1]
	v_mov_b32_e32 v82, v87
	v_pk_fma_f32 v[80:81], v[4:5], v[82:83], v[80:81] op_sel_hi:[0,1,1]
	v_pk_add_f32 v[64:65], v[64:65], v[80:81]
	v_add_u32_e32 v3, 0x10010, v78
	ds_read_b128 v[80:83], v78 offset:61456
	ds_read_b128 v[84:87], v3
	v_add_u32_e32 v78, 32, v78
	s_waitcnt lgkmcnt(1)
	v_mov_b32_e32 v89, v80
	s_waitcnt lgkmcnt(0)
	v_mov_b32_e32 v80, v85
	v_mov_b32_e32 v88, v84
	v_pk_mul_f32 v[2:3], v[2:3], v[80:81] op_sel_hi:[0,1]
	v_pk_fma_f32 v[2:3], v[66:67], v[88:89], v[2:3] op_sel_hi:[0,1,1]
	v_mov_b32_e32 v66, v86
	v_mov_b32_e32 v67, v82
	v_pk_fma_f32 v[2:3], v[68:69], v[66:67], v[2:3] op_sel_hi:[0,1,1]
	v_mov_b32_e32 v82, v87
	v_pk_fma_f32 v[2:3], v[4:5], v[82:83], v[2:3] op_sel_hi:[0,1,1]
	v_pk_add_f32 v[8:9], v[8:9], v[2:3]
	s_cbranch_scc0 .LBB0_63
	s_barrier
	ds_write2st64_b32 v74, v16, v11 offset1:1
	ds_write2st64_b32 v74, v10, v13 offset0:2 offset1:3
	ds_write2st64_b32 v74, v12, v57 offset0:4 offset1:5
	ds_write2st64_b32 v74, v56, v59 offset0:6 offset1:7
	ds_write2st64_b32 v74, v58, v61 offset0:8 offset1:9
	ds_write2st64_b32 v74, v60, v63 offset0:10 offset1:11
	ds_write2st64_b32 v74, v62, v65 offset0:12 offset1:13
	ds_write2st64_b32 v74, v64, v9 offset0:14 offset1:15
	ds_write_b32 v74, v8 offset:4096
	s_waitcnt lgkmcnt(0)
	s_barrier
	s_and_saveexec_b64 s[0:1], s[6:7]
	s_cbranch_execz .LBB0_7
	s_mul_i32 s4, s2, 0xffffffa0
	s_add_i32 s4, s4, s64
	s_load_dwordx16 s[36:51], s[74:75], 0x0
	s_lshl_b32 s8, s4, 6
	s_add_i32 s3, s8, s3
	v_or_b32_e32 v2, s3, v71
	s_ashr_i32 s9, s8, 31
	v_ashrrev_i32_e32 v3, 31, v2
	s_mul_i32 s4, s2, 17
	s_waitcnt lgkmcnt(0)
	v_lshl_add_u64 v[2:3], v[2:3], 2, s[46:47]
	v_lshl_add_u64 v[4:5], s[8:9], 2, v[30:31]
	s_mov_b64 s[2:3], 0
	v_mov_b32_e32 v6, v73
	v_mov_b32_e32 v7, v14

;   const int tid = opaque_tid(), lane = tid & 63, wave = tid >> 6;
;   for (int m = bid * 4 + wave; m < MALL; m += nb * 4) {
;     const int b = m / TALL, t = m - b * TALL;
;     const bool isctx = t < CTX;
;     const int tp = t - CTX, rowp = tp >> 6, colp = tp & 63;
;     u16* pr = P.pbuf + (size_t)m * INW;
;     float xv[22];
; #pragma unroll
;     for (int ch = 0; ch < 22; ++ch) {
;       const int col = ch < 4 ? 960 + ch * 64 : (ch < 6 ? 1216 + (ch - 4) * 64 : (ch < 10 ? 1472 + (ch - 6) * 64 : (ch < 14 ? 1728 + (ch - 10) * 64 : (ch < 18 ? 2240 + (ch - 14) * 64 : 2496 + (ch - 18) * 64))));
;       xv[ch] = bf2f(pr[col + lane]);
;     }
;     float csA = 1.f, snA = 0.f, csD = 1.f, snD = 0.f, csR = 1.f, snR = 0.f;
;     if (!isctx) {
;       { const int e = lane & 31, pos = (lane >> 5) ? colp : rowp, i = e & 15; csA = P.ropeA[(pos * 16 + i) * 2]; snA = P.ropeA[(pos * 16 + i) * 2 + 1]; if (e < 16) snA = -snA; }
;       { const int e = lane & 15, pos = ((lane >> 4) & 1) ? colp : rowp, i = e & 7; csD = P.ropeD[(pos * 8 + i) * 2]; snD = P.ropeD[(pos * 8 + i) * 2 + 1]; if (e < 8) snD = -snD; }
;       { const int i = lane & 31; csR = P.ropeR[(tp * 32 + i) * 2]; snR = P.ropeR[(tp * 32 + i) * 2 + 1]; if (lane < 32) snR = -snR; }
;     }
;     const float gq = P.gqa_q_norm[l * 64 + lane], gk = P.gqa_k_norm[l * 64 + lane];
; #pragma unroll
;     for (int ch = 0; ch < 22; ++ch) {
;       const int col = ch < 4 ? 960 + ch * 64 : (ch < 6 ? 1216 + (ch - 4) * 64 : (ch < 10 ? 1472 + (ch - 6) * 64 : (ch < 14 ? 1728 + (ch - 10) * 64 : (ch < 18 ? 2240 + (ch - 14) * 64 : 2496 + (ch - 18) * 64))));
;       float x = xv[ch];
;       if (ch < 6) {
;         const float ss = wave_sum(x * x);
;         x = x * rsqrtf(ss * (1.f / 64.f) + 1e-6f) * (ch < 4 ? gq : gk);
;         const float partner = __shfl_xor(x, 16);
;         x = x * csA + partner * snA;
;         if (ch < 4) x *= 0.125f * LOG2E;
;       } else if (ch < 14) {
;         const float partner = __shfl_xor(x, 8);
;         x = x * csD + partner * snD;
;         if (ch < 10) x *= 0.17677669529663687f * LOG2E;
;       } else {
;         const float partner = __shfl_xor(x, 32);
;         x = x * csR + partner * snR;
;         if (ch >= 18) x *= 0.125f;
;       }
;       if (dummy) { asm volatile("" :: "v"(x)); x = xv[ch]; }
;       pr[col + lane] = f2bf(x);
.LBB0_561:
	s_or_b64 exec, exec, s[12:13]
	v_readlane_b32 s88, v251, 29
	s_nop 1
	v_add_u32_e32 v87, s88, v26
	v_min_i32_e32 v87, 0x8fff, v87
	s_movk_i32 s88, 0x1980
	v_mad_i64_i32 v[88:89], s[90:91], v87, s88, v[0:1]
	s_mov_b64 s[92:93], 0x1000
	v_lshl_add_u64 v[90:91], v[88:89], 0, s[92:93]
	global_load_ushort v65, v[88:89], off offset:1920
	global_load_ushort v66, v[88:89], off offset:2048
	global_load_ushort v67, v[88:89], off offset:2176
	global_load_ushort v68, v[88:89], off offset:2304
	global_load_ushort v69, v[88:89], off offset:2432
	global_load_ushort v70, v[88:89], off offset:2560
	global_load_ushort v71, v[88:89], off offset:2944
	global_load_ushort v72, v[88:89], off offset:3072
	global_load_ushort v73, v[88:89], off offset:3200
	global_load_ushort v74, v[88:89], off offset:3328
	global_load_ushort v75, v[88:89], off offset:3456
	global_load_ushort v76, v[88:89], off offset:3584
	global_load_ushort v77, v[88:89], off offset:3712
	global_load_ushort v78, v[88:89], off offset:3840
	global_load_ushort v79, v[90:91], off offset:384
	global_load_ushort v80, v[90:91], off offset:512
	global_load_ushort v81, v[90:91], off offset:640
	global_load_ushort v82, v[90:91], off offset:768
	global_load_ushort v83, v[90:91], off offset:896
	global_load_ushort v84, v[90:91], off offset:1024
	global_load_ushort v85, v[90:91], off offset:1152
	global_load_ushort v86, v[90:91], off offset:1280
	s_mov_b32 s90, 0xffff
	s_mov_b32 s91, 0xffff
	s_mov_b32 s92, -1
	s_mov_b32 s93, 0
	s_mov_b64 s[12:13], 0x1180
	s_nop 0
	v_lshlrev_b32_e32 v57, 16, v38
	v_lshl_add_u64 v[22:23], v[4:5], 0, s[12:13]
	s_mov_b64 s[12:13], 0x1200
	s_nop 0
	v_lshlrev_b32_e32 v58, 16, v39
	v_mul_f32_e32 v38, v57, v57
	v_lshl_add_u64 v[20:21], v[4:5], 0, s[12:13]
	s_mov_b64 s[12:13], 0x1280
	s_nop 0
	v_lshlrev_b32_e32 v59, 16, v40
	v_mov_b32_dpp v38, v38 quad_perm:[1,0,3,2] row_mask:0xf bank_mask:0xf bound_ctrl:1
	v_mul_f32_e32 v40, v58, v58
	v_lshl_add_u64 v[18:19], v[4:5], 0, s[12:13]
	s_mov_b64 s[12:13], 0x1300
	v_fmac_f32_e32 v38, v57, v57
	v_mov_b32_dpp v40, v40 quad_perm:[1,0,3,2] row_mask:0xf bank_mask:0xf bound_ctrl:1
	v_lshl_add_u64 v[14:15], v[4:5], 0, s[12:13]
	s_mov_b64 s[12:13], 0x1380
	v_add_f32_dpp v38, v38, v38 quad_perm:[2,3,0,1] row_mask:0xf bank_mask:0xf bound_ctrl:1
	v_fmac_f32_e32 v40, v58, v58
	v_lshl_add_u64 v[12:13], v[4:5], 0, s[12:13]
	s_mov_b64 s[12:13], 0x1400
	v_add_f32_dpp v38, v38, v38 row_half_mirror row_mask:0xf bank_mask:0xf bound_ctrl:1
	v_add_f32_dpp v40, v40, v40 quad_perm:[2,3,0,1] row_mask:0xf bank_mask:0xf bound_ctrl:1
	v_lshl_add_u64 v[10:11], v[4:5], 0, s[12:13]
	s_mov_b64 s[12:13], 0x1480
	v_add_f32_dpp v38, v38, v38 row_mirror row_mask:0xf bank_mask:0xf bound_ctrl:1
	v_add_f32_dpp v40, v40, v40 row_half_mirror row_mask:0xf bank_mask:0xf bound_ctrl:1
	v_lshl_add_u64 v[8:9], v[4:5], 0, s[12:13]
	s_mov_b64 s[12:13], 0x1500
	v_readlane_b32 s14, v38, 16
	v_readlane_b32 s15, v38, 48
	v_add_f32_dpp v40, v40, v40 row_mirror row_mask:0xf bank_mask:0xf bound_ctrl:1
	v_lshl_add_u64 v[6:7], v[4:5], 0, s[12:13]
	v_readlane_b32 s12, v38, 0
	v_readlane_b32 s13, v38, 32
	v_mov_b32_e32 v38, s14
	v_mov_b32_e32 v39, s15
	v_readlane_b32 s14, v40, 16
	v_readlane_b32 s15, v40, 48
	s_nop 0
	v_lshlrev_b32_e32 v60, 16, v41
	v_pk_add_f32 v[38:39], s[12:13], v[38:39]
	v_readlane_b32 s12, v40, 0
	v_readlane_b32 s13, v40, 32
	v_mov_b32_e32 v40, s14
	v_mov_b32_e32 v41, s15
	v_pk_add_f32 v[40:41], s[12:13], v[40:41]
	s_nop 0
	v_lshlrev_b32_e32 v61, 16, v42
	s_nop 0
	v_lshlrev_b32_e32 v62, 16, v43
	v_mov_b32_e32 v42, v40
	v_mov_b32_e32 v43, v38
	v_mov_b32_e32 v38, v41
	s_mov_b32 s12, 0x358637bd
	v_pk_add_f32 v[38:39], v[42:43], v[38:39]
	v_mov_b64_e32 v[40:41], s[12:13]
	s_mov_b32 s18, 0x3c800000
	v_pk_fma_f32 v[38:39], v[38:39], s[18:19], v[40:41] op_sel_hi:[1,0,0]
	s_mov_b32 s16, 0x800000
	v_mul_f32_e32 v42, 0x4b800000, v39
	v_cmp_gt_f32_e32 vcc, s16, v39
	s_nop 0
	v_lshlrev_b32_e32 v63, 16, v36
	s_nop 0
	v_lshlrev_b32_e32 v64, 16, v37
	v_cndmask_b32_e32 v39, v39, v42, vcc
	v_rsq_f32_e32 v39, v39
	s_movk_i32 s17, 0x7fff
	v_lshlrev_b32_e32 v44, 16, v44
	v_lshlrev_b32_e32 v45, 16, v45
	v_mul_f32_e32 v36, 0x45800000, v39
	v_cndmask_b32_e32 v36, v39, v36, vcc
	v_mul_f32_e32 v36, v36, v57
	v_mul_f32_e32 v36, v27, v36
	v_mul_f32_e32 v39, 0x4b800000, v38
	v_cmp_gt_f32_e32 vcc, s16, v38
	v_mov_b32_e32 v88, v36
	v_mov_b32_e32 v89, v36
	s_nop 1
	v_permlane16_swap_b32_e32 v88, v89
	v_cndmask_b32_e64 v37, v88, v89, s[90:91]
	v_mul_f32_e32 v36, v24, v36
	v_cndmask_b32_e32 v38, v38, v39, vcc
	v_rsq_f32_e32 v38, v38
	v_lshlrev_b32_e32 v46, 16, v46
	s_waitcnt lgkmcnt(0)
	v_fmac_f32_e32 v36, v25, v37
	v_mul_f32_e32 v36, 0x3e38aa3b, v36
	v_mul_f32_e32 v37, 0x45800000, v38
	v_cndmask_b32_e32 v37, v38, v37, vcc
	v_mul_f32_e32 v37, v37, v58
	v_mul_f32_e32 v37, v27, v37
	v_mov_b32_e32 v88, v37
	v_mov_b32_e32 v89, v37
	s_nop 1
	v_permlane16_swap_b32_e32 v88, v89
	v_cndmask_b32_e64 v38, v88, v89, s[90:91]
	v_bfe_u32 v39, v36, 16, 1
	v_add3_u32 v36, v36, v39, s17
	global_store_short_d16_hi v[4:5], v36, off offset:1920
	v_mul_f32_e32 v36, v24, v37
	s_waitcnt lgkmcnt(0)
;     ...
;     for (int ch = 0; ch < 22; ++ch) {
;       const int col = ch < 4 ? 960 + ch * 64 : (ch < 6 ? 1216 + (ch - 4) * 64 : (ch < 10 ? 1472 + (ch - 6) * 64 : (ch < 14 ? 1728 + (ch - 10) * 64 : (ch < 18 ? 2240 + (ch - 14) * 64 : 2496 + (ch - 18) * 64))));
;       float x = xv[ch];
;       if (ch < 6) {
;         const float ss = wave_sum(x * x);
;         x = x * rsqrtf(ss * (1.f / 64.f) + 1e-6f) * (ch < 4 ? gq : gk);
;         const float partner = __shfl_xor(x, 16);
;         x = x * csA + partner * snA;
;         if (ch < 4) x *= 0.125f * LOG2E;
;       } else if (ch < 14) {
;         const float partner = __shfl_xor(x, 8);
;         x = x * csD + partner * snD;
;         if (ch < 10) x *= 0.17677669529663687f * LOG2E;
	v_fmac_f32_e32 v36, v25, v38
	v_mul_f32_e32 v57, 0x3e38aa3b, v36
	v_mul_f32_e32 v36, v59, v59
	v_mul_f32_e32 v38, v60, v60
	v_lshlrev_b32_e32 v47, 16, v47
	v_mov_b32_dpp v36, v36 quad_perm:[1,0,3,2] row_mask:0xf bank_mask:0xf bound_ctrl:1
	v_fmac_f32_e32 v36, v59, v59
	v_mov_b32_dpp v38, v38 quad_perm:[1,0,3,2] row_mask:0xf bank_mask:0xf bound_ctrl:1
	v_fmac_f32_e32 v38, v60, v60
	v_add_f32_dpp v36, v36, v36 quad_perm:[2,3,0,1] row_mask:0xf bank_mask:0xf bound_ctrl:1
	v_lshlrev_b32_e32 v48, 16, v48
	v_add_f32_dpp v38, v38, v38 quad_perm:[2,3,0,1] row_mask:0xf bank_mask:0xf bound_ctrl:1
	v_add_f32_dpp v36, v36, v36 row_half_mirror row_mask:0xf bank_mask:0xf bound_ctrl:1
	v_lshlrev_b32_e32 v49, 16, v49
	v_add_f32_dpp v38, v38, v38 row_half_mirror row_mask:0xf bank_mask:0xf bound_ctrl:1
	v_add_f32_dpp v36, v36, v36 row_mirror row_mask:0xf bank_mask:0xf bound_ctrl:1
	v_lshlrev_b32_e32 v50, 16, v50
	v_readlane_b32 s14, v36, 16
	v_readlane_b32 s15, v36, 48
	v_add_f32_dpp v38, v38, v38 row_mirror row_mask:0xf bank_mask:0xf bound_ctrl:1
	v_readlane_b32 s12, v36, 0
	v_readlane_b32 s13, v36, 32
	v_mov_b32_e32 v36, s14
	v_mov_b32_e32 v37, s15
	v_readlane_b32 s14, v38, 16
	v_readlane_b32 s15, v38, 48
	v_pk_add_f32 v[36:37], s[12:13], v[36:37]
	v_readlane_b32 s12, v38, 0
	v_readlane_b32 s13, v38, 32
	v_mov_b32_e32 v38, s14
	v_mov_b32_e32 v39, s15
	v_pk_add_f32 v[38:39], s[12:13], v[38:39]
	v_mov_b32_e32 v43, v36
	v_mov_b32_e32 v42, v38
	v_mov_b32_e32 v36, v39
	v_pk_add_f32 v[36:37], v[42:43], v[36:37]
	v_lshlrev_b32_e32 v51, 16, v51
	v_pk_fma_f32 v[36:37], v[36:37], s[18:19], v[40:41] op_sel_hi:[1,0,0]
	v_lshlrev_b32_e32 v52, 16, v52
	v_mul_f32_e32 v38, 0x4b800000, v37
	v_cmp_gt_f32_e32 vcc, s16, v37
	v_mul_f32_e32 v39, 0x4b800000, v36
	v_lshlrev_b32_e32 v53, 16, v53
	v_cndmask_b32_e32 v37, v37, v38, vcc
	v_rsq_f32_e32 v37, v37
	v_bfe_u32 v38, v57, 16, 1
	v_add3_u32 v38, v57, v38, s17
	global_store_short_d16_hi v[4:5], v38, off offset:2048
	v_mul_f32_e32 v38, 0x45800000, v37
	v_cndmask_b32_e32 v37, v37, v38, vcc
	v_mul_f32_e32 v37, v37, v59
	v_mul_f32_e32 v37, v27, v37
	v_cmp_gt_f32_e32 vcc, s16, v36
	v_mov_b32_e32 v88, v37
	v_mov_b32_e32 v89, v37
	s_nop 1
	v_permlane16_swap_b32_e32 v88, v89
	v_cndmask_b32_e64 v38, v88, v89, s[90:91]
	v_mul_f32_e32 v37, v24, v37
	v_cndmask_b32_e32 v36, v36, v39, vcc
	v_rsq_f32_e32 v36, v36
	v_lshlrev_b32_e32 v54, 16, v54
	s_waitcnt lgkmcnt(0)
	v_fmac_f32_e32 v37, v25, v38
	v_mul_f32_e32 v37, 0x3e38aa3b, v37
	v_mul_f32_e32 v38, 0x45800000, v36
	v_cndmask_b32_e32 v36, v36, v38, vcc
	v_mul_f32_e32 v36, v36, v60
	v_mul_f32_e32 v36, v27, v36
	v_mov_b32_e32 v88, v36
	v_mov_b32_e32 v89, v36
	s_nop 1
	v_permlane16_swap_b32_e32 v88, v89
	v_cndmask_b32_e64 v38, v88, v89, s[90:91]
	v_mul_f32_e32 v36, v24, v36
	v_bfe_u32 v39, v37, 16, 1
	v_add3_u32 v37, v37, v39, s17
	global_store_short_d16_hi v[4:5], v37, off offset:2176
	s_waitcnt lgkmcnt(0)
	v_fmac_f32_e32 v36, v25, v38
	v_mul_f32_e32 v57, 0x3e38aa3b, v36
	v_mul_f32_e32 v36, v61, v61
	v_mul_f32_e32 v38, v62, v62
	v_lshlrev_b32_e32 v55, 16, v55
	v_mov_b32_dpp v36, v36 quad_perm:[1,0,3,2] row_mask:0xf bank_mask:0xf bound_ctrl:1
	v_fmac_f32_e32 v36, v61, v61
	v_mov_b32_dpp v38, v38 quad_perm:[1,0,3,2] row_mask:0xf bank_mask:0xf bound_ctrl:1
	v_fmac_f32_e32 v38, v62, v62
	v_add_f32_dpp v36, v36, v36 quad_perm:[2,3,0,1] row_mask:0xf bank_mask:0xf bound_ctrl:1
	v_lshlrev_b32_e32 v56, 16, v56
	v_add_f32_dpp v38, v38, v38 quad_perm:[2,3,0,1] row_mask:0xf bank_mask:0xf bound_ctrl:1
	v_add_f32_dpp v36, v36, v36 row_half_mirror row_mask:0xf bank_mask:0xf bound_ctrl:1
	v_lshlrev_b32_e32 v35, 16, v35
	v_add_f32_dpp v38, v38, v38 row_half_mirror row_mask:0xf bank_mask:0xf bound_ctrl:1
	v_add_f32_dpp v36, v36, v36 row_mirror row_mask:0xf bank_mask:0xf bound_ctrl:1
	s_nop 0
	v_readlane_b32 s14, v36, 16
	v_readlane_b32 s15, v36, 48
	v_add_f32_dpp v38, v38, v38 row_mirror row_mask:0xf bank_mask:0xf bound_ctrl:1
	v_readlane_b32 s12, v36, 0
	v_readlane_b32 s13, v36, 32
	v_mov_b32_e32 v36, s14
	v_mov_b32_e32 v37, s15
	v_readlane_b32 s14, v38, 16
	v_readlane_b32 s15, v38, 48
	v_pk_add_f32 v[36:37], s[12:13], v[36:37]
	v_readlane_b32 s12, v38, 0
	v_readlane_b32 s13, v38, 32
	v_mov_b32_e32 v38, s14
	v_mov_b32_e32 v39, s15
	v_pk_add_f32 v[38:39], s[12:13], v[38:39]
	v_mov_b32_e32 v43, v36
	v_mov_b32_e32 v42, v38
	v_mov_b32_e32 v36, v39
	v_pk_add_f32 v[36:37], v[42:43], v[36:37]
	v_readlane_b32 s12, v251, 29
	v_pk_fma_f32 v[36:37], v[36:37], s[18:19], v[40:41] op_sel_hi:[1,0,0]
	v_readlane_b32 s13, v251, 30
	v_mul_f32_e32 v38, 0x4b800000, v37
	v_cmp_gt_f32_e32 vcc, s16, v37
	v_mul_f32_e32 v39, 0x4b800000, v36
	v_add_u32_e32 v26, s12, v26
	v_cndmask_b32_e32 v37, v37, v38, vcc
	v_rsq_f32_e32 v37, v37
	v_bfe_u32 v38, v57, 16, 1
	v_add3_u32 v38, v57, v38, s17
	global_store_short_d16_hi v[4:5], v38, off offset:2304
	v_mul_f32_e32 v38, 0x45800000, v37
	v_cndmask_b32_e32 v37, v37, v38, vcc
	v_cmp_gt_f32_e32 vcc, s16, v36
	v_mul_f32_e32 v37, v37, v61
	v_mul_f32_e32 v37, v28, v37
	v_cndmask_b32_e32 v36, v36, v39, vcc
	v_rsq_f32_e32 v36, v36
	v_mov_b32_e32 v88, v37
	v_mov_b32_e32 v89, v37
	s_nop 1
	v_permlane16_swap_b32_e32 v88, v89
	v_cndmask_b32_e64 v38, v88, v89, s[90:91]
	v_mul_f32_e32 v37, v24, v37
	s_mov_b32 s12, 0x8fff
	v_mul_f32_e32 v39, 0x45800000, v36
	v_cndmask_b32_e32 v36, v36, v39, vcc
	v_mul_f32_e32 v36, v36, v62
	v_mul_f32_e32 v36, v28, v36
	v_mov_b32_e32 v88, v36
	v_mov_b32_e32 v89, v36
	s_nop 1
	v_permlane16_swap_b32_e32 v88, v89
	v_cndmask_b32_e64 v39, v88, v89, s[90:91]
	v_mul_f32_e32 v24, v24, v36
	s_nop 1
	v_mov_b32_dpp v36, v44 row_ror:8 row_mask:0xf bank_mask:0xf
	s_waitcnt lgkmcnt(2)
; DI u16 f2bf(float x) { unsigned u = __float_as_uint(x); u += 0x7fffu + ((u >> 16) & 1u); return (u16)(u >> 16); }
;     ...
;       } else if (ch < 14) {
;         const float partner = __shfl_xor(x, 8);
;         x = x * csD + partner * snD;
;         if (ch < 10) x *= 0.17677669529663687f * LOG2E;
;       } else {
;         const float partner = __shfl_xor(x, 32);
;         x = x * csR + partner * snR;
;         if (ch >= 18) x *= 0.125f;
;       }
;       if (dummy) { asm volatile("" :: "v"(x)); x = xv[ch]; }
;       pr[col + lane] = f2bf(x);
;     }
;   }
	v_fmac_f32_e32 v37, v25, v38
	v_bfe_u32 v38, v37, 16, 1
	s_waitcnt lgkmcnt(1)
	v_fmac_f32_e32 v24, v25, v39
	v_bfe_u32 v25, v24, 16, 1
	v_add3_u32 v24, v24, v25, s17
	global_store_short_d16_hi v[4:5], v24, off offset:2560
	s_waitcnt lgkmcnt(0)
	v_mul_f32_e32 v24, v17, v36
	s_nop 1
	v_mov_b32_dpp v25, v45 row_ror:8 row_mask:0xf bank_mask:0xf
	v_fmac_f32_e32 v24, v16, v44
	v_mul_f32_e32 v24, 0x3e8293ee, v24
	v_bfe_u32 v36, v24, 16, 1
	v_add3_u32 v24, v24, v36, s17
	global_store_short_d16_hi v[4:5], v24, off offset:2944
	s_waitcnt lgkmcnt(0)
	v_mul_f32_e32 v24, v17, v25
	s_nop 1
	v_mov_b32_dpp v25, v46 row_ror:8 row_mask:0xf bank_mask:0xf
	v_fmac_f32_e32 v24, v16, v45
	v_mul_f32_e32 v24, 0x3e8293ee, v24
	v_bfe_u32 v36, v24, 16, 1
	v_add3_u32 v24, v24, v36, s17
	global_store_short_d16_hi v[4:5], v24, off offset:3072
	s_waitcnt lgkmcnt(0)
	v_mul_f32_e32 v24, v17, v25
	s_nop 1
	v_mov_b32_dpp v25, v47 row_ror:8 row_mask:0xf bank_mask:0xf
	v_fmac_f32_e32 v24, v16, v46
	v_mul_f32_e32 v24, 0x3e8293ee, v24
	v_bfe_u32 v36, v24, 16, 1
	v_add3_u32 v24, v24, v36, s17
	global_store_short_d16_hi v[4:5], v24, off offset:3200
	s_waitcnt lgkmcnt(0)
	v_mul_f32_e32 v24, v17, v25
	s_nop 1
	v_mov_b32_dpp v25, v48 row_ror:8 row_mask:0xf bank_mask:0xf
	v_fmac_f32_e32 v24, v16, v47
	v_mul_f32_e32 v24, 0x3e8293ee, v24
	v_bfe_u32 v36, v24, 16, 1
	v_add3_u32 v24, v24, v36, s17
	global_store_short_d16_hi v[4:5], v24, off offset:3328
	s_waitcnt lgkmcnt(0)
	v_mul_f32_e32 v24, v17, v25
	s_nop 1
	v_mov_b32_dpp v25, v49 row_ror:8 row_mask:0xf bank_mask:0xf
	v_fmac_f32_e32 v24, v16, v48
	v_bfe_u32 v36, v24, 16, 1
	v_add3_u32 v24, v24, v36, s17
	global_store_short_d16_hi v[4:5], v24, off offset:3456
	s_waitcnt lgkmcnt(0)
	v_mul_f32_e32 v24, v17, v25
	s_nop 1
	v_mov_b32_dpp v25, v50 row_ror:8 row_mask:0xf bank_mask:0xf
	v_fmac_f32_e32 v24, v16, v49
	v_bfe_u32 v36, v24, 16, 1
	v_add3_u32 v24, v24, v36, s17
	global_store_short_d16_hi v[4:5], v24, off offset:3584
	s_waitcnt lgkmcnt(0)
	v_mul_f32_e32 v24, v17, v25
	s_nop 1
	v_mov_b32_dpp v25, v51 row_ror:8 row_mask:0xf bank_mask:0xf
	v_fmac_f32_e32 v24, v16, v50
	v_bfe_u32 v36, v24, 16, 1
	v_add3_u32 v24, v24, v36, s17
	global_store_short_d16_hi v[4:5], v24, off offset:3712
	s_waitcnt lgkmcnt(0)
	v_mul_f32_e32 v17, v17, v25
	v_mov_b32_e32 v88, v52
	v_mov_b32_e32 v89, v52
	s_nop 1
	v_permlane32_swap_b32_e32 v88, v89
	v_cndmask_b32_e64 v24, v88, v89, s[92:93]
	v_fmac_f32_e32 v17, v16, v51
	v_bfe_u32 v16, v17, 16, 1
	v_add3_u32 v37, v37, v38, s17
	v_add3_u32 v16, v17, v16, s17
	global_store_short_d16_hi v[4:5], v37, off offset:2432
	global_store_short_d16_hi v[4:5], v16, off offset:3840
	v_mov_b32_e32 v88, v53
	v_mov_b32_e32 v89, v53
	s_nop 1
	v_permlane32_swap_b32_e32 v88, v89
	v_cndmask_b32_e64 v5, v88, v89, s[92:93]
	s_waitcnt lgkmcnt(1)
	v_mul_f32_e32 v4, v3, v24
	v_fmac_f32_e32 v4, v2, v52
	v_bfe_u32 v16, v4, 16, 1
	v_add3_u32 v4, v4, v16, s17
	global_store_short_d16_hi v[22:23], v4, off
	s_waitcnt lgkmcnt(0)
	v_mul_f32_e32 v4, v3, v5
	v_mov_b32_e32 v88, v54
	v_mov_b32_e32 v89, v54
	s_nop 1
	v_permlane32_swap_b32_e32 v88, v89
	v_cndmask_b32_e64 v5, v88, v89, s[92:93]
	v_fmac_f32_e32 v4, v2, v53
	v_bfe_u32 v16, v4, 16, 1
	v_add3_u32 v4, v4, v16, s17
	global_store_short_d16_hi v[20:21], v4, off
	s_waitcnt lgkmcnt(0)
	v_mul_f32_e32 v4, v3, v5
	v_mov_b32_e32 v88, v55
	v_mov_b32_e32 v89, v55
	s_nop 1
	v_permlane32_swap_b32_e32 v88, v89
	v_cndmask_b32_e64 v5, v88, v89, s[92:93]
	v_fmac_f32_e32 v4, v2, v54
	v_bfe_u32 v16, v4, 16, 1
	v_add3_u32 v4, v4, v16, s17
	global_store_short_d16_hi v[18:19], v4, off
	s_waitcnt lgkmcnt(0)
	v_mul_f32_e32 v4, v3, v5
	v_mov_b32_e32 v88, v56
	v_mov_b32_e32 v89, v56
	s_nop 1
	v_permlane32_swap_b32_e32 v88, v89
	v_cndmask_b32_e64 v5, v88, v89, s[92:93]
	v_fmac_f32_e32 v4, v2, v55
	v_bfe_u32 v16, v4, 16, 1
	v_add3_u32 v4, v4, v16, s17
	global_store_short_d16_hi v[14:15], v4, off
	s_waitcnt lgkmcnt(0)
	v_mul_f32_e32 v4, v3, v5
	v_mov_b32_e32 v88, v35
	v_mov_b32_e32 v89, v35
	s_nop 1
	v_permlane32_swap_b32_e32 v88, v89
	v_cndmask_b32_e64 v5, v88, v89, s[92:93]
	v_fmac_f32_e32 v4, v2, v56
	v_mul_f32_e32 v4, 0x3e000000, v4
	v_bfe_u32 v14, v4, 16, 1
	v_add3_u32 v4, v4, v14, s17
	global_store_short_d16_hi v[12:13], v4, off
	s_waitcnt lgkmcnt(0)
	v_mul_f32_e32 v4, v3, v5
	v_mov_b32_e32 v88, v63
	v_mov_b32_e32 v89, v63
	s_nop 1
	v_permlane32_swap_b32_e32 v88, v89
	v_cndmask_b32_e64 v5, v88, v89, s[92:93]
	v_fmac_f32_e32 v4, v2, v35
	v_mul_f32_e32 v4, 0x3e000000, v4
	v_bfe_u32 v12, v4, 16, 1
	v_add3_u32 v4, v4, v12, s17
	global_store_short_d16_hi v[10:11], v4, off
	s_waitcnt lgkmcnt(0)
	v_mul_f32_e32 v4, v3, v5
	v_mov_b32_e32 v88, v64
	v_mov_b32_e32 v89, v64
	s_nop 1
	v_permlane32_swap_b32_e32 v88, v89
	v_cndmask_b32_e64 v5, v88, v89, s[92:93]
	v_fmac_f32_e32 v4, v2, v63
	v_mul_f32_e32 v4, 0x3e000000, v4
	v_bfe_u32 v10, v4, 16, 1
	v_cmp_lt_i32_e32 vcc, s12, v26
	s_waitcnt lgkmcnt(0)
	v_mul_f32_e32 v3, v3, v5
	v_fmac_f32_e32 v3, v2, v64
	v_mul_f32_e32 v2, 0x3e000000, v3
	v_bfe_u32 v3, v2, 16, 1
	v_add3_u32 v4, v4, v10, s17
	v_add3_u32 v2, v2, v3, s17
	s_or_b64 s[10:11], vcc, s[10:11]
	global_store_short_d16_hi v[8:9], v4, off
	global_store_short_d16_hi v[6:7], v2, off
	s_andn2_b64 exec, exec, s[10:11]
	s_cbranch_execz .LBB0_594
